# workgroup-local seams (state->scan, scan->out) use only vmcnt(0)+s_barrier: same-workgroup hand-off needs no agent-scope invalidate (tg_split=0, one CU, one L1)
# baseline (speedup 1.0000x reference)
.LBB0_252:
	s_mov_b64 s[6:7], s[84:85]
	s_mov_b32 s3, s72
	v_mbcnt_lo_u32_b32 v0, -1, 0
	v_mbcnt_hi_u32_b32 v0, -1, v0
	s_getreg_b32 s2, hwreg(HW_REG_HW_ID, 0, 6)
	s_lshl_b32 s2, s2, 2
	s_and_b32 s2, s2, 0xfc
	s_add_i32 s2, s2, 0
	s_add_i32 s2, s2, 0x23400
	v_mov_b32_e32 v2, s2
	ds_read_b32 v2, v2
	s_waitcnt vmcnt(0) lgkmcnt(0)
	v_sub_u32_e32 v0, 0, v0
	s_waitcnt vmcnt(0) lgkmcnt(0)
	s_barrier
	v_readfirstlane_b32 s2, v2
	s_lshl_b32 s2, s2, 6
	s_nop 0
	v_cmp_eq_u32_e32 vcc, s2, v0
	s_mov_b64 s[4:5], exec
	s_branch .LBB0_320
	v_mov_b32_e32 v0, s86
	s_load_dwordx2 s[6:7], s[6:7], 0x110
	s_getreg_b32 s2, hwreg(HW_REG_XCC_ID, 0, 4)
	ds_read_b32 v3, v0
	v_mov_b32_e32 v0, s87
	ds_read_b32 v2, v0
	s_and_b32 s2, s2, 15
	s_waitcnt lgkmcnt(0)
	v_cmp_ne_u32_e32 vcc, 0, v3
	s_cbranch_vccnz .LBB0_262
	s_add_u32 s8, s6, 0x4400
	s_addc_u32 s9, s7, 0
	s_add_u32 s10, s6, 0x4500
	s_addc_u32 s11, s7, 0
	s_add_u32 s12, s6, 0x4600
	s_addc_u32 s13, s7, 0
	s_add_u32 s14, s6, 0x4700
	s_addc_u32 s15, s7, 0
	s_add_u32 s16, s6, 0x4800
	s_addc_u32 s17, s7, 0
	s_add_u32 s18, s6, 0x4900
	s_addc_u32 s19, s7, 0
	s_add_u32 s20, s6, 0x4a00
	s_addc_u32 s21, s7, 0
	s_add_u32 s22, s6, 0x4b00
	s_addc_u32 s23, s7, 0
	s_add_u32 s24, s6, 0x4c00
	s_addc_u32 s25, s7, 0
	s_add_u32 s26, s6, 0x4d00
	s_addc_u32 s27, s7, 0
	s_add_u32 s28, s6, 0x4e00
	s_addc_u32 s29, s7, 0
	s_add_u32 s30, s6, 0x4f00
	s_addc_u32 s31, s7, 0
	s_add_u32 s34, s6, 0x5000
	s_addc_u32 s35, s7, 0
	s_add_u32 s36, s6, 0x5100
	s_addc_u32 s37, s7, 0
	s_add_u32 s38, s6, 0x5200
	s_addc_u32 s39, s7, 0
	s_add_u32 s40, s6, 0x5300
	s_addc_u32 s41, s7, 0
	s_mov_b32 s45, 0x400000
	s_branch .LBB0_257

.LBB0_326:
	s_or_b64 exec, exec, s[10:11]
	s_mov_b64 s[6:7], s[84:85]
	s_mov_b32 s3, s72
	v_mbcnt_lo_u32_b32 v0, -1, 0
	v_mbcnt_hi_u32_b32 v0, -1, v0
	s_getreg_b32 s2, hwreg(HW_REG_HW_ID, 0, 6)
	s_lshl_b32 s2, s2, 2
	s_and_b32 s2, s2, 0xfc
	s_add_i32 s2, s2, 0
	s_add_i32 s2, s2, 0x23400
	v_mov_b32_e32 v2, s2
	ds_read_b32 v2, v2
	s_waitcnt vmcnt(0) lgkmcnt(0)
	v_sub_u32_e32 v0, 0, v0
	s_waitcnt lgkmcnt(0)
	s_barrier
	v_readfirstlane_b32 s2, v2
	s_lshl_b32 s2, s2, 6
	s_nop 0
	v_cmp_eq_u32_e32 vcc, s2, v0
	s_mov_b64 s[4:5], exec
	s_branch .LBB0_394
	v_mov_b32_e32 v0, s86
	s_load_dwordx2 s[6:7], s[6:7], 0x110
	s_getreg_b32 s2, hwreg(HW_REG_XCC_ID, 0, 4)
	ds_read_b32 v3, v0
	v_mov_b32_e32 v0, s87
	ds_read_b32 v2, v0
	s_and_b32 s2, s2, 15
	s_waitcnt lgkmcnt(0)
	v_cmp_ne_u32_e32 vcc, 0, v3
	s_cbranch_vccnz .LBB0_336
	s_add_u32 s8, s6, 0x4400
	s_addc_u32 s9, s7, 0
	s_add_u32 s10, s6, 0x4500
	s_addc_u32 s11, s7, 0
	s_add_u32 s12, s6, 0x4600
	s_addc_u32 s13, s7, 0
	s_add_u32 s14, s6, 0x4700
	s_addc_u32 s15, s7, 0
	s_add_u32 s16, s6, 0x4800
	s_addc_u32 s17, s7, 0
	s_add_u32 s18, s6, 0x4900
	s_addc_u32 s19, s7, 0
	s_add_u32 s20, s6, 0x4a00
	s_addc_u32 s21, s7, 0
	s_add_u32 s22, s6, 0x4b00
	s_addc_u32 s23, s7, 0
	s_add_u32 s24, s6, 0x4c00
	s_addc_u32 s25, s7, 0
	s_add_u32 s26, s6, 0x4d00
	s_addc_u32 s27, s7, 0
	s_add_u32 s28, s6, 0x4e00
	s_addc_u32 s29, s7, 0
	s_add_u32 s30, s6, 0x4f00
	s_addc_u32 s31, s7, 0
	s_add_u32 s34, s6, 0x5000
	s_addc_u32 s35, s7, 0
	s_add_u32 s36, s6, 0x5100
	s_addc_u32 s37, s7, 0
	s_add_u32 s38, s6, 0x5200
	s_addc_u32 s39, s7, 0
	s_add_u32 s40, s6, 0x5300
	s_addc_u32 s41, s7, 0
	s_mov_b32 s45, 0x400000
	s_branch .LBB0_331
